# P0 gain values fetched with the tile (no serial load chain between LDS writes); P6 prologue load batches no longer drained mid-batch; stage_dt bias load joins its batch
# baseline (speedup 1.0000x reference)
.LBB0_13:
	s_andn2_b64 vcc, exec, s[0:1]
	s_cbranch_vccnz .LBB0_39
	v_readlane_b32 s52, v253, 41
	s_mul_i32 s1, s12, 0x5800000
	v_readlane_b32 s58, v253, 47
	s_mul_hi_i32 s0, s12, 0x5800000
	v_readlane_b32 s59, v253, 48
	s_add_u32 s16, s58, s1
	s_addc_u32 s17, s59, s0
	s_lshl_b32 s0, s12, 11
	s_ashr_i32 s1, s0, 31
	v_readlane_b32 s56, v253, 45
	s_lshl_b64 s[0:1], s[0:1], 2
	v_readlane_b32 s57, v253, 46
	s_add_u32 s14, s56, s0
	s_addc_u32 s15, s57, s1
	s_add_i32 s0, s20, 0xefe0
	s_and_b32 s1, s0, 0xffff
	s_mul_i32 s1, s1, 0xba2f
	s_lshr_b32 s1, s1, 23
	s_mul_i32 s13, s1, 0xb0
	s_sub_i32 s13, s0, s13
	s_lshl_b32 s0, s13, 8
	s_lshl_b32 s18, s1, 6
	s_and_b32 s0, s0, 0x3ff00
	s_add_u32 s0, s16, s0
	v_or_b32_e32 v74, s18, v67
	s_addc_u32 s1, s17, 0
	v_mov_b32_e32 v73, v69
	v_lshl_add_u64 v[2:3], s[0:1], 0, v[72:73]
	v_mul_u32_u24_e32 v68, 0xb000, v74
	v_lshl_add_u64 v[2:3], v[2:3], 0, v[68:69]
	s_mov_b32 s0, 0x2c000
	v_add_co_u32_e32 v4, vcc, s0, v2
	s_mov_b32 s0, 0x84000
	s_nop 0
	v_addc_co_u32_e32 v5, vcc, 0, v3, vcc
	global_load_dwordx4 v[62:65], v[2:3], off nt
	global_load_dwordx4 v[58:61], v[4:5], off nt
	v_add_co_u32_e32 v4, vcc, s43, v2
	v_cndmask_b32_e64 v68, 0, 1, s[4:5]
	s_nop 0
	v_addc_co_u32_e32 v5, vcc, 0, v3, vcc
	v_add_co_u32_e32 v6, vcc, s0, v2
	s_mov_b32 s0, 0xb0000
	s_nop 0
	v_addc_co_u32_e32 v7, vcc, 0, v3, vcc
	global_load_dwordx4 v[54:57], v[4:5], off nt
	global_load_dwordx4 v[50:53], v[6:7], off nt
	v_add_co_u32_e32 v4, vcc, s0, v2
	s_mov_b32 s0, 0xdc000
	s_nop 0
	v_addc_co_u32_e32 v5, vcc, 0, v3, vcc
	v_add_co_u32_e32 v6, vcc, s0, v2
	s_mov_b32 s0, 0x108000
	s_nop 0
	v_addc_co_u32_e32 v7, vcc, 0, v3, vcc
	global_load_dwordx4 v[46:49], v[4:5], off nt
	global_load_dwordx4 v[42:45], v[6:7], off nt
	v_add_co_u32_e32 v4, vcc, s0, v2
	s_mov_b32 s0, 0x134000
	s_nop 0
	v_addc_co_u32_e32 v5, vcc, 0, v3, vcc
	v_add_co_u32_e32 v6, vcc, s0, v2
	s_mov_b32 s0, 0x160000
	s_nop 0
	v_addc_co_u32_e32 v7, vcc, 0, v3, vcc
	global_load_dwordx4 v[38:41], v[4:5], off nt
	global_load_dwordx4 v[34:37], v[6:7], off nt
	v_add_co_u32_e32 v4, vcc, s0, v2
	s_mov_b32 s0, 0x18c000
	s_nop 0
	v_addc_co_u32_e32 v5, vcc, 0, v3, vcc
	v_add_co_u32_e32 v6, vcc, s0, v2
	s_mov_b32 s0, 0x1b8000
	s_nop 0
	v_addc_co_u32_e32 v7, vcc, 0, v3, vcc
	global_load_dwordx4 v[30:33], v[4:5], off nt
	global_load_dwordx4 v[26:29], v[6:7], off nt
	v_add_co_u32_e32 v4, vcc, s0, v2
	s_mov_b32 s0, 0x1e4000
	s_nop 0
	v_addc_co_u32_e32 v5, vcc, 0, v3, vcc
	v_add_co_u32_e32 v6, vcc, s0, v2
	s_mov_b32 s0, 0x210000
	s_nop 0
	v_addc_co_u32_e32 v7, vcc, 0, v3, vcc
	global_load_dwordx4 v[22:25], v[4:5], off nt
	global_load_dwordx4 v[18:21], v[6:7], off nt
	v_add_co_u32_e32 v4, vcc, s0, v2
	v_cmp_ne_u32_e64 s[0:1], 1, v68
	s_nop 0
	v_addc_co_u32_e32 v5, vcc, 0, v3, vcc
	v_add_co_u32_e32 v6, vcc, 0x23c000, v2
	v_add_lshl_u32 v73, v67, s18, 2
	s_nop 0
	v_addc_co_u32_e32 v7, vcc, 0, v3, vcc
	global_load_dwordx4 v[14:17], v[4:5], off nt
	global_load_dwordx4 v[10:13], v[6:7], off nt
	v_add_co_u32_e32 v4, vcc, 0x268000, v2
	v_readlane_b32 s53, v253, 42
	s_nop 0
	v_addc_co_u32_e32 v5, vcc, 0, v3, vcc
	v_add_co_u32_e32 v2, vcc, 0x294000, v2
	v_readlane_b32 s54, v253, 43
	s_nop 0
	v_addc_co_u32_e32 v3, vcc, 0, v3, vcc
	global_load_dwordx4 v[6:9], v[4:5], off nt
	s_nop 0
	global_load_dwordx4 v[2:5], v[2:3], off nt
	s_andn2_b64 vcc, exec, s[4:5]
	v_readlane_b32 s55, v253, 44
	v_readlane_b32 s60, v253, 49
	v_readlane_b32 s61, v253, 50
	v_readlane_b32 s62, v253, 51
	v_readlane_b32 s63, v253, 52
	v_readlane_b32 s64, v253, 53
	v_readlane_b32 s65, v253, 54
	v_readlane_b32 s66, v253, 55
	v_readlane_b32 s67, v253, 56
	s_cbranch_vccnz .LBB0_156
	global_load_dword v144, v73, s[14:15]
	global_load_dword v145, v73, s[14:15] offset:16
	global_load_dword v146, v73, s[14:15] offset:32
	global_load_dword v147, v73, s[14:15] offset:48
	global_load_dword v148, v73, s[14:15] offset:64
	global_load_dword v149, v73, s[14:15] offset:80
	global_load_dword v150, v73, s[14:15] offset:96
	global_load_dword v151, v73, s[14:15] offset:112
	global_load_dword v152, v73, s[14:15] offset:128
	global_load_dword v153, v73, s[14:15] offset:144
	global_load_dword v154, v73, s[14:15] offset:160
	global_load_dword v155, v73, s[14:15] offset:176
	global_load_dword v156, v73, s[14:15] offset:192
	global_load_dword v157, v73, s[14:15] offset:208
	global_load_dword v158, v73, s[14:15] offset:224
	global_load_dword v159, v73, s[14:15] offset:240
	s_waitcnt vmcnt(0)
	v_lshlrev_b32_e32 v68, 2, v74
	v_mov_b32_e32 v74, v144
	s_nop 0
	v_mov_b32_e32 v68, v145
	s_waitcnt vmcnt(0)
	v_pk_mul_f32 v[142:143], v[62:63], v[74:75] op_sel_hi:[1,0]
	v_pk_mul_f32 v[74:75], v[64:65], v[74:75] op_sel_hi:[1,0]
	ds_write2_b32 v97, v142, v143 offset1:1
	ds_write2_b32 v97, v74, v75 offset0:2 offset1:3
	s_cbranch_execnz .LBB0_17

.LBB0_17:
	s_waitcnt vmcnt(0)
	v_pk_mul_f32 v[58:59], v[58:59], v[68:69] op_sel_hi:[1,0]
	v_add_u32_e32 v62, v71, v86
	ds_write2_b32 v62, v58, v59 offset1:1
	v_pk_mul_f32 v[58:59], v[60:61], v[68:69] op_sel_hi:[1,0]
	s_and_b64 vcc, exec, s[0:1]
	ds_write2_b32 v62, v58, v59 offset0:2 offset1:3
	s_cbranch_vccnz .LBB0_157
	v_mov_b32_e32 v60, v146
	v_mov_b32_e32 v58, v147
	v_add_u32_e32 v59, v71, v87
	s_waitcnt vmcnt(1)
	v_pk_mul_f32 v[62:63], v[54:55], v[60:61] op_sel_hi:[1,0]
	v_pk_mul_f32 v[60:61], v[56:57], v[60:61] op_sel_hi:[1,0]
	ds_write2_b32 v59, v62, v63 offset1:1
	ds_write2_b32 v59, v60, v61 offset0:2 offset1:3
	s_cbranch_execnz .LBB0_20

.LBB0_20:
	s_waitcnt vmcnt(0)
	v_pk_mul_f32 v[50:51], v[50:51], v[58:59] op_sel_hi:[1,0]
	v_add_u32_e32 v54, v71, v88
	ds_write2_b32 v54, v50, v51 offset1:1
	v_pk_mul_f32 v[50:51], v[52:53], v[58:59] op_sel_hi:[1,0]
	s_and_b64 vcc, exec, s[0:1]
	ds_write2_b32 v54, v50, v51 offset0:2 offset1:3
	s_cbranch_vccnz .LBB0_158
	v_mov_b32_e32 v52, v148
	v_mov_b32_e32 v50, v149
	v_add_u32_e32 v51, v71, v89
	s_waitcnt vmcnt(1)
	v_pk_mul_f32 v[54:55], v[46:47], v[52:53] op_sel_hi:[1,0]
	v_pk_mul_f32 v[52:53], v[48:49], v[52:53] op_sel_hi:[1,0]
	ds_write2_b32 v51, v54, v55 offset1:1
	ds_write2_b32 v51, v52, v53 offset0:2 offset1:3
	s_cbranch_execnz .LBB0_23

.LBB0_23:
	s_waitcnt vmcnt(0)
	v_pk_mul_f32 v[42:43], v[42:43], v[50:51] op_sel_hi:[1,0]
	v_add_u32_e32 v46, v71, v90
	ds_write2_b32 v46, v42, v43 offset1:1
	v_pk_mul_f32 v[42:43], v[44:45], v[50:51] op_sel_hi:[1,0]
	s_and_b64 vcc, exec, s[0:1]
	ds_write2_b32 v46, v42, v43 offset0:2 offset1:3
	s_cbranch_vccnz .LBB0_159
	v_mov_b32_e32 v44, v150
	v_mov_b32_e32 v42, v151
	v_add_u32_e32 v43, v71, v91
	s_waitcnt vmcnt(1)
	v_pk_mul_f32 v[46:47], v[38:39], v[44:45] op_sel_hi:[1,0]
	v_pk_mul_f32 v[44:45], v[40:41], v[44:45] op_sel_hi:[1,0]
	ds_write2_b32 v43, v46, v47 offset1:1
	ds_write2_b32 v43, v44, v45 offset0:2 offset1:3
	s_cbranch_execnz .LBB0_26

.LBB0_26:
	s_waitcnt vmcnt(0)
	v_pk_mul_f32 v[34:35], v[34:35], v[42:43] op_sel_hi:[1,0]
	v_add_u32_e32 v38, v71, v92
	ds_write2_b32 v38, v34, v35 offset1:1
	v_pk_mul_f32 v[34:35], v[36:37], v[42:43] op_sel_hi:[1,0]
	s_and_b64 vcc, exec, s[0:1]
	ds_write2_b32 v38, v34, v35 offset0:2 offset1:3
	s_cbranch_vccnz .LBB0_160
	v_mov_b32_e32 v36, v152
	v_mov_b32_e32 v34, v153
	v_add_u32_e32 v35, v71, v93
	s_waitcnt vmcnt(1)
	v_pk_mul_f32 v[38:39], v[30:31], v[36:37] op_sel_hi:[1,0]
	v_pk_mul_f32 v[36:37], v[32:33], v[36:37] op_sel_hi:[1,0]
	ds_write2_b32 v35, v38, v39 offset1:1
	ds_write2_b32 v35, v36, v37 offset0:2 offset1:3
	s_cbranch_execnz .LBB0_29

.LBB0_29:
	s_waitcnt vmcnt(0)
	v_pk_mul_f32 v[26:27], v[26:27], v[34:35] op_sel_hi:[1,0]
	v_add_u32_e32 v30, v71, v94
	ds_write2_b32 v30, v26, v27 offset1:1
	v_pk_mul_f32 v[26:27], v[28:29], v[34:35] op_sel_hi:[1,0]
	s_and_b64 vcc, exec, s[0:1]
	ds_write2_b32 v30, v26, v27 offset0:2 offset1:3
	s_cbranch_vccnz .LBB0_161
	v_mov_b32_e32 v28, v154
	v_mov_b32_e32 v26, v155
	v_add_u32_e32 v27, v71, v95
	s_waitcnt vmcnt(1)
	v_pk_mul_f32 v[30:31], v[22:23], v[28:29] op_sel_hi:[1,0]
	v_pk_mul_f32 v[28:29], v[24:25], v[28:29] op_sel_hi:[1,0]
	ds_write2_b32 v27, v30, v31 offset1:1
	ds_write2_b32 v27, v28, v29 offset0:2 offset1:3
	s_cbranch_execnz .LBB0_32

.LBB0_32:
	s_waitcnt vmcnt(0)
	v_pk_mul_f32 v[22:23], v[18:19], v[26:27] op_sel_hi:[1,0]
	v_add_u32_e32 v19, v71, v96
	v_pk_mul_f32 v[20:21], v[20:21], v[26:27] op_sel_hi:[1,0]
	ds_write2_b32 v19, v20, v21 offset0:2 offset1:3
	s_and_b64 vcc, exec, s[0:1]
	v_add_u32_e32 v20, 0x410, v19
	v_add_u32_e32 v21, 0x418, v19
	ds_write2_b32 v19, v22, v23 offset1:1
	s_cbranch_vccnz .LBB0_162
	v_mov_b32_e32 v22, v156
	v_mov_b32_e32 v18, v157
	s_waitcnt vmcnt(1)
	v_pk_mul_f32 v[24:25], v[14:15], v[22:23] op_sel_hi:[1,0]
	v_pk_mul_f32 v[22:23], v[16:17], v[22:23] op_sel_hi:[1,0]
	ds_write2_b32 v20, v24, v25 offset1:1
	ds_write2_b32 v21, v22, v23 offset1:1
	s_cbranch_execnz .LBB0_35

.LBB0_35:
	s_waitcnt vmcnt(0)
	v_pk_mul_f32 v[10:11], v[10:11], v[18:19] op_sel_hi:[1,0]
	v_add_u32_e32 v14, 0x820, v19
	ds_write2_b32 v14, v10, v11 offset1:1
	v_pk_mul_f32 v[10:11], v[12:13], v[18:19] op_sel_hi:[1,0]
	v_add_u32_e32 v12, 0x828, v19
	ds_write2_b32 v12, v10, v11 offset1:1
	s_and_b64 vcc, exec, s[0:1]
	v_add_u32_e32 v11, 0xc30, v19
	v_add_u32_e32 v12, 0xc38, v19
	s_cbranch_vccnz .LBB0_163
	v_mov_b32_e32 v14, v158
	v_mov_b32_e32 v10, v159
	s_waitcnt vmcnt(1)
	v_pk_mul_f32 v[16:17], v[6:7], v[14:15] op_sel_hi:[1,0]
	v_pk_mul_f32 v[14:15], v[8:9], v[14:15] op_sel_hi:[1,0]
	ds_write2_b32 v11, v16, v17 offset1:1
	ds_write2_b32 v12, v14, v15 offset1:1
	s_cbranch_execnz .LBB0_38

.LBB0_266:
	s_ashr_i32 s9, s8, 31
	s_lshl_b64 s[4:5], s[8:9], 12
	v_lshl_add_u64 v[144:145], v[50:51], 0, s[4:5]
	v_add_co_u32_e32 v152, vcc, 0x8000, v144
	global_load_dwordx4 v[4:7], v[144:145], off
	global_load_dwordx4 v[8:11], v[24:25], off
	v_addc_co_u32_e32 v153, vcc, 0, v145, vcc
	v_add_co_u32_e32 v160, vcc, 0x10000, v144
	global_load_dwordx4 v[12:15], v[152:153], off
	s_nop 0
	v_addc_co_u32_e32 v161, vcc, 0, v145, vcc
	global_load_dwordx4 v[16:19], v[160:161], off
	global_load_dwordx4 v[56:59], v[26:27], off
	global_load_dwordx4 v[60:63], v[28:29], off
	global_load_dwordx4 v[64:67], v[30:31], off
	v_add_co_u32_e32 v164, vcc, 0x18000, v144
	v_add_u32_e32 v55, s20, v52
	s_nop 0
	v_addc_co_u32_e32 v165, vcc, 0, v145, vcc
	global_load_dwordx4 v[68:71], v[164:165], off
	global_load_dwordx4 v[72:75], v[144:145], off offset:128
	global_load_dwordx4 v[76:79], v[24:25], off offset:128
	global_load_dwordx4 v[80:83], v[152:153], off offset:128
	global_load_dwordx4 v[84:87], v[32:33], off
	global_load_dwordx4 v[88:91], v[160:161], off offset:128
	global_load_dwordx4 v[92:95], v[34:35], off
	global_load_dwordx4 v[96:99], v[164:165], off offset:128
	global_load_dwordx4 v[100:103], v[36:37], off
	global_load_dwordx4 v[104:107], v[38:39], off
	global_load_dwordx4 v[108:111], v[40:41], off
	global_load_dwordx4 v[112:115], v[24:25], off offset:256
	global_load_dwordx4 v[116:119], v[24:25], off offset:384
	global_load_dwordx4 v[120:123], v[42:43], off
	global_load_dwordx4 v[124:127], v[44:45], off
	global_load_dwordx4 v[128:131], v[144:145], off offset:256
	global_load_dwordx4 v[132:135], v[46:47], off
	global_load_dwordx4 v[136:139], v[48:49], off
	global_load_dwordx4 v[140:143], v[152:153], off offset:256
	s_nop 0
	global_load_dwordx4 v[144:147], v[144:145], off offset:384
	s_nop 0
	global_load_dwordx4 v[148:151], v[160:161], off offset:256
	s_nop 0
	global_load_dwordx4 v[152:155], v[152:153], off offset:384
	s_nop 0
	global_load_dwordx4 v[156:159], v[164:165], off offset:256
	s_nop 0
	global_load_dwordx4 v[160:163], v[160:161], off offset:384
	s_nop 0
	global_load_dwordx4 v[164:167], v[164:165], off offset:384
	s_waitcnt vmcnt(0)
	ds_write_b128 v53, v[8:11] offset:4608
	ds_write_b128 v53, v[56:59] offset:5760
	ds_write_b128 v53, v[60:63] offset:6912
	ds_write_b128 v53, v[64:67] offset:8064
	ds_write_b128 v53, v[4:7]
	ds_write_b128 v53, v[12:15] offset:1152
	ds_write_b128 v53, v[16:19] offset:2304
	ds_write_b128 v53, v[68:71] offset:3456
	s_waitcnt lgkmcnt(0)
	ds_read_b128 v[4:7], v54
	ds_read_b128 v[8:11], v54 offset:4608
	ds_read_b128 v[56:59], v54 offset:16
	ds_read_b128 v[60:63], v54 offset:4624
	s_waitcnt lgkmcnt(2)
	v_mfma_f32_32x32x16_bf16 v[4:19], v[4:7], v[8:11], 0
	s_waitcnt lgkmcnt(0)
	v_mfma_f32_32x32x16_bf16 v[4:19], v[56:59], v[60:63], v[4:19]
	ds_read_b128 v[56:59], v54 offset:32
	ds_read_b128 v[60:63], v54 offset:4640
	ds_read_b128 v[64:67], v54 offset:48
	ds_read_b128 v[68:71], v54 offset:4656
	ds_write_b128 v53, v[72:75]
	ds_write_b128 v53, v[76:79] offset:4608
	ds_write_b128 v53, v[80:83] offset:1152
	ds_write_b128 v53, v[84:87] offset:5760
	ds_write_b128 v53, v[88:91] offset:2304
	ds_write_b128 v53, v[92:95] offset:6912
	ds_write_b128 v53, v[96:99] offset:3456
	ds_write_b128 v53, v[100:103] offset:8064
	s_waitcnt lgkmcnt(0)
	s_waitcnt lgkmcnt(10)
	v_mfma_f32_32x32x16_bf16 v[4:19], v[56:59], v[60:63], v[4:19]
	s_waitcnt lgkmcnt(8)
	v_mfma_f32_32x32x16_bf16 v[4:19], v[64:67], v[68:71], v[4:19]
	ds_read_b128 v[56:59], v54
	ds_read_b128 v[60:63], v54 offset:4608
	ds_read_b128 v[64:67], v54 offset:16
	ds_read_b128 v[68:71], v54 offset:4624
	s_waitcnt lgkmcnt(2)
	v_mfma_f32_32x32x16_bf16 v[4:19], v[56:59], v[60:63], v[4:19]
	s_waitcnt lgkmcnt(0)
	v_mfma_f32_32x32x16_bf16 v[4:19], v[64:67], v[68:71], v[4:19]
	ds_read_b128 v[56:59], v54 offset:32
	ds_read_b128 v[60:63], v54 offset:4640
	ds_read_b128 v[64:67], v54 offset:48
	ds_read_b128 v[68:71], v54 offset:4656
	ds_write_b128 v53, v[128:131]
	ds_write_b128 v53, v[112:115] offset:4608
	ds_write_b128 v53, v[140:143] offset:1152
	ds_write_b128 v53, v[104:107] offset:5760
	ds_write_b128 v53, v[148:151] offset:2304
	ds_write_b128 v53, v[108:111] offset:6912
	ds_write_b128 v53, v[156:159] offset:3456
	ds_write_b128 v53, v[120:123] offset:8064
	s_waitcnt lgkmcnt(0)
	s_waitcnt lgkmcnt(10)
	v_mfma_f32_32x32x16_bf16 v[4:19], v[56:59], v[60:63], v[4:19]
	s_waitcnt lgkmcnt(8)
	v_mfma_f32_32x32x16_bf16 v[4:19], v[64:67], v[68:71], v[4:19]
	ds_read_b128 v[56:59], v54
	ds_read_b128 v[60:63], v54 offset:4608
	ds_read_b128 v[64:67], v54 offset:16
	ds_read_b128 v[68:71], v54 offset:4624
	s_waitcnt lgkmcnt(2)
	v_mfma_f32_32x32x16_bf16 v[4:19], v[56:59], v[60:63], v[4:19]
	s_waitcnt lgkmcnt(0)
	v_mfma_f32_32x32x16_bf16 v[4:19], v[64:67], v[68:71], v[4:19]
	ds_read_b128 v[56:59], v54 offset:32
	ds_read_b128 v[60:63], v54 offset:4640
	ds_read_b128 v[64:67], v54 offset:48
	ds_read_b128 v[68:71], v54 offset:4656
	ds_write_b128 v53, v[144:147]
	ds_write_b128 v53, v[116:119] offset:4608
	ds_write_b128 v53, v[152:155] offset:1152
	ds_write_b128 v53, v[124:127] offset:5760
	ds_write_b128 v53, v[160:163] offset:2304
	ds_write_b128 v53, v[132:135] offset:6912
	ds_write_b128 v53, v[164:167] offset:3456
	ds_write_b128 v53, v[136:139] offset:8064
	s_waitcnt lgkmcnt(0)
	s_waitcnt lgkmcnt(10)
	v_mfma_f32_32x32x16_bf16 v[4:19], v[56:59], v[60:63], v[4:19]
	s_waitcnt lgkmcnt(8)
	v_mfma_f32_32x32x16_bf16 v[4:19], v[64:67], v[68:71], v[4:19]
	ds_read_b128 v[56:59], v54
	ds_read_b128 v[60:63], v54 offset:4608
	ds_read_b128 v[64:67], v54 offset:16
	ds_read_b128 v[68:71], v54 offset:4624
	s_waitcnt lgkmcnt(2)
	v_mfma_f32_32x32x16_bf16 v[4:19], v[56:59], v[60:63], v[4:19]
	s_waitcnt lgkmcnt(0)
	v_mfma_f32_32x32x16_bf16 v[4:19], v[64:67], v[68:71], v[4:19]
	ds_read_b128 v[56:59], v54 offset:32
	ds_read_b128 v[60:63], v54 offset:4640
	ds_read_b128 v[64:67], v54 offset:48
	ds_read_b128 v[68:71], v54 offset:4656
	s_waitcnt lgkmcnt(2)
	v_mfma_f32_32x32x16_bf16 v[4:19], v[56:59], v[60:63], v[4:19]
	s_waitcnt lgkmcnt(0)
	v_mfma_f32_32x32x16_bf16 v[4:19], v[64:67], v[68:71], v[4:19]
	s_nop 11
	ds_write2st64_b32 v55, v4, v5 offset1:1
	ds_write2st64_b32 v55, v6, v7 offset0:2 offset1:3
	ds_write2st64_b32 v55, v8, v9 offset0:4 offset1:5
	ds_write2st64_b32 v55, v10, v11 offset0:6 offset1:7
	ds_write2st64_b32 v55, v12, v13 offset0:8 offset1:9
	ds_write2st64_b32 v55, v14, v15 offset0:10 offset1:11
	ds_write2st64_b32 v55, v16, v17 offset0:12 offset1:13
	ds_write2st64_b32 v55, v18, v19 offset0:14 offset1:15
	s_waitcnt lgkmcnt(0)
	s_waitcnt lgkmcnt(0)
	s_barrier
	s_and_saveexec_b64 s[18:19], s[6:7]
	s_cbranch_execz .LBB0_265
	v_add_u32_e32 v11, s21, v52
	ds_read2st64_b32 v[4:5], v11 offset0:2 offset1:3
	ds_read2st64_b32 v[6:7], v11 offset0:18 offset1:19
	ds_read2st64_b32 v[8:9], v11 offset0:34 offset1:35
	ds_read2st64_b32 v[12:13], v11 offset0:50 offset1:51
	ds_read2st64_b32 v[14:15], v11 offset0:66 offset1:67
	ds_read2st64_b32 v[16:17], v11 offset0:82 offset1:83
	ds_read2st64_b32 v[18:19], v11 offset0:98 offset1:99
	ds_read2st64_b32 v[56:57], v11 offset0:114 offset1:115
	s_waitcnt lgkmcnt(7)
	v_add_f32_e32 v5, 0, v5
	v_add_f32_e32 v4, 0, v4
	s_waitcnt lgkmcnt(6)
	v_add_f32_e32 v5, v5, v7
	v_add_f32_e32 v4, v4, v6
	s_waitcnt lgkmcnt(5)
	v_add_f32_e32 v5, v5, v9
	v_add_f32_e32 v4, v4, v8
	s_waitcnt lgkmcnt(4)
	v_add_f32_e32 v5, v5, v13
	v_add_f32_e32 v4, v4, v12
	s_waitcnt lgkmcnt(3)
	v_add_f32_e32 v5, v5, v15
	v_add_f32_e32 v4, v4, v14
	s_waitcnt lgkmcnt(2)
	v_add_f32_e32 v5, v5, v17
	v_add_f32_e32 v4, v4, v16
	s_waitcnt lgkmcnt(1)
	v_add_f32_e32 v5, v5, v19
	v_add_f32_e32 v4, v4, v18
	s_waitcnt lgkmcnt(0)
	v_add_f32_e32 v5, v5, v57
	v_add_f32_e32 v4, v4, v56
	v_add_f32_e32 v10, 0, v5
	v_add_f32_e32 v12, 0, v4
	ds_read2st64_b32 v[4:5], v11 offset1:1
	ds_read2st64_b32 v[6:7], v11 offset0:16 offset1:17
	ds_read2st64_b32 v[8:9], v11 offset0:32 offset1:33
	ds_read2st64_b32 v[14:15], v11 offset0:48 offset1:49
	ds_read2st64_b32 v[16:17], v11 offset0:64 offset1:65
	ds_read2st64_b32 v[18:19], v11 offset0:80 offset1:81
	ds_read2st64_b32 v[56:57], v11 offset0:96 offset1:97
	ds_read2st64_b32 v[58:59], v11 offset0:112 offset1:113
	s_waitcnt lgkmcnt(7)
	v_add_f32_e32 v4, 0, v4
	v_add_f32_e32 v5, 0, v5
	s_waitcnt lgkmcnt(6)
	v_add_f32_e32 v4, v4, v6
	v_add_f32_e32 v5, v5, v7
	s_waitcnt lgkmcnt(5)
	v_add_f32_e32 v4, v4, v8
	v_add_f32_e32 v5, v5, v9
	s_waitcnt lgkmcnt(4)
	v_add_f32_e32 v4, v4, v14
	v_add_f32_e32 v5, v5, v15
	s_waitcnt lgkmcnt(3)
	v_add_f32_e32 v4, v4, v16
	v_add_f32_e32 v5, v5, v17
	s_waitcnt lgkmcnt(2)
	v_add_f32_e32 v4, v4, v18
	v_add_f32_e32 v5, v5, v19
	s_waitcnt lgkmcnt(1)
	v_add_f32_e32 v4, v4, v56
	v_add_f32_e32 v5, v5, v57
	s_waitcnt lgkmcnt(0)
	v_add_f32_e32 v4, v4, v58
	v_add_f32_e32 v5, v5, v59
	v_add_f32_e32 v14, 0, v4
	v_add_u32_e32 v4, s8, v2
	v_add_f32_e32 v13, 0, v5
	v_ashrrev_i32_e32 v5, 31, v4
	v_lshl_add_u64 v[6:7], v[4:5], 2, s[16:17]
	v_mov_b32_e32 v220, v6
	v_mov_b32_e32 v221, v7
	v_add_co_u32_e32 v222, vcc, s23, v6
	s_nop 1
	v_addc_co_u32_e32 v223, vcc, 0, v7, vcc
	v_add_co_u32_e32 v224, vcc, s78, v6
	s_nop 1
	v_addc_co_u32_e32 v225, vcc, 0, v7, vcc
	v_add_co_u32_e32 v226, vcc, s24, v6
	s_nop 1
	v_addc_co_u32_e32 v227, vcc, 0, v7, vcc
	v_add_co_u32_e32 v228, vcc, s25, v6
	s_nop 1
	v_addc_co_u32_e32 v229, vcc, 0, v7, vcc
	v_add_co_u32_e32 v230, vcc, s26, v6
	s_nop 1
	v_addc_co_u32_e32 v231, vcc, 0, v7, vcc
	v_add_co_u32_e32 v232, vcc, s27, v6
	s_nop 1
	v_addc_co_u32_e32 v233, vcc, 0, v7, vcc
	v_add_co_u32_e32 v234, vcc, s28, v6
	s_nop 1
	v_addc_co_u32_e32 v235, vcc, 0, v7, vcc
	global_load_dword v176, v[220:221], off
	global_load_dword v177, v[222:223], off offset:128
	global_load_dword v178, v[224:225], off offset:256
	global_load_dword v179, v[226:227], off offset:384
	global_load_dword v180, v[228:229], off offset:512
	global_load_dword v181, v[230:231], off offset:640
	global_load_dword v182, v[232:233], off offset:768
	global_load_dword v183, v[234:235], off offset:896
	global_load_dword v184, v[220:221], off offset:4
	global_load_dword v185, v[222:223], off offset:132
	global_load_dword v186, v[224:225], off offset:260
	global_load_dword v187, v[226:227], off offset:388
	global_load_dword v188, v[228:229], off offset:516
	global_load_dword v189, v[230:231], off offset:644
	global_load_dword v190, v[232:233], off offset:772
	global_load_dword v191, v[234:235], off offset:900
	global_load_dword v192, v[220:221], off offset:8
	global_load_dword v193, v[222:223], off offset:136
	global_load_dword v194, v[224:225], off offset:264
	global_load_dword v195, v[226:227], off offset:392
	global_load_dword v196, v[228:229], off offset:520
	global_load_dword v197, v[230:231], off offset:648
	global_load_dword v198, v[232:233], off offset:776
	global_load_dword v199, v[234:235], off offset:904
	global_load_dword v200, v[220:221], off offset:12
	global_load_dword v201, v[222:223], off offset:140
	global_load_dword v202, v[224:225], off offset:268
	global_load_dword v203, v[226:227], off offset:396
	global_load_dword v204, v[228:229], off offset:524
	global_load_dword v205, v[230:231], off offset:652
	global_load_dword v206, v[232:233], off offset:780
	global_load_dword v207, v[234:235], off offset:908
	global_load_dword v11, v[20:21], off
	s_waitcnt vmcnt(0)
	v_mov_b32_e32 v8, v176
	s_mov_b32 s9, 0xbfb8aa3b
	s_waitcnt vmcnt(0) lgkmcnt(0)
	v_add_f32_e32 v15, 0, v8
	v_add_co_u32_e32 v8, vcc, s23, v6
	s_nop 1
	v_addc_co_u32_e32 v9, vcc, 0, v7, vcc
	v_mov_b32_e32 v8, v177
	s_waitcnt vmcnt(0) lgkmcnt(0)
	v_add_f32_e32 v15, v15, v8
	v_add_co_u32_e32 v8, vcc, s78, v6
	s_nop 1
	v_addc_co_u32_e32 v9, vcc, 0, v7, vcc
	v_mov_b32_e32 v8, v178
	s_waitcnt vmcnt(0) lgkmcnt(0)
	v_add_f32_e32 v15, v15, v8
	v_add_co_u32_e32 v8, vcc, s24, v6
	s_nop 1
	v_addc_co_u32_e32 v9, vcc, 0, v7, vcc
	v_mov_b32_e32 v8, v179
	s_waitcnt vmcnt(0) lgkmcnt(0)
	v_add_f32_e32 v15, v15, v8
	v_add_co_u32_e32 v8, vcc, s25, v6
	s_nop 1
	v_addc_co_u32_e32 v9, vcc, 0, v7, vcc
	v_mov_b32_e32 v8, v180
	s_waitcnt vmcnt(0) lgkmcnt(0)
	v_add_f32_e32 v15, v15, v8
	v_add_co_u32_e32 v8, vcc, s26, v6
	s_nop 1
	v_addc_co_u32_e32 v9, vcc, 0, v7, vcc
	v_mov_b32_e32 v8, v181
	s_waitcnt vmcnt(0) lgkmcnt(0)
	v_add_f32_e32 v15, v15, v8
	v_add_co_u32_e32 v8, vcc, s27, v6
	s_nop 1
	v_addc_co_u32_e32 v9, vcc, 0, v7, vcc
	v_add_co_u32_e32 v6, vcc, s28, v6
	v_mov_b32_e32 v8, v182
	s_nop 0
	v_addc_co_u32_e32 v7, vcc, 0, v7, vcc
	v_mov_b32_e32 v6, v183
	v_add_f32_e32 v8, v15, v8
	v_add_f32_e32 v6, v8, v6
	v_fmamk_f32 v6, v6, 0x3a000000, v214
	v_cmp_gt_f32_e32 vcc, s79, v6
	v_mul_f32_e32 v7, 0x4f800000, v6
	s_nop 0
	v_cndmask_b32_e32 v6, v6, v7, vcc
	v_sqrt_f32_e32 v7, v6
	s_nop 0
	v_add_u32_e32 v8, -1, v7
	v_fma_f32 v9, -v8, v7, v6
	v_cmp_ge_f32_e64 s[4:5], 0, v9
	v_add_u32_e32 v9, 1, v7
	s_nop 0
	v_cndmask_b32_e64 v8, v7, v8, s[4:5]
	v_fma_f32 v7, -v9, v7, v6
	v_cmp_lt_f32_e64 s[4:5], 0, v7
	s_nop 1
	v_cndmask_b32_e64 v7, v8, v9, s[4:5]
	v_mul_f32_e32 v8, 0x37800000, v7
	v_cndmask_b32_e32 v7, v7, v8, vcc
	v_cmp_class_f32_e32 vcc, v6, v1
	s_nop 1
	v_cndmask_b32_e32 v6, v7, v6, vcc
	v_div_scale_f32 v7, s[4:5], v6, v6, v14
	v_rcp_f32_e32 v8, v7
	s_nop 0
	v_fma_f32 v9, -v7, v8, 1.0
	v_fmac_f32_e32 v8, v9, v8
	v_div_scale_f32 v9, vcc, v14, v6, v14
	v_mul_f32_e32 v15, v9, v8
	v_fma_f32 v16, -v7, v15, v9
	v_fmac_f32_e32 v15, v16, v8
	v_fma_f32 v7, -v7, v15, v9
	v_div_fmas_f32 v7, v7, v8, v15
	v_div_fixup_f32 v6, v7, v6, v14
	v_add_f32_e32 v6, v11, v6
	v_max_f32_e32 v8, 0, v6
	v_mul_f32_e64 v6, |v6|, s9
	v_exp_f32_e32 v6, v6
	s_nop 0
	v_add_f32_e32 v6, 1.0, v6
	v_log_f32_e32 v6, v6
	s_nop 0
	v_fmac_f32_e32 v8, 0x3f317218, v6
	v_lshlrev_b64 v[6:7], 6, v[4:5]
	v_lshl_add_u64 v[6:7], v[22:23], 0, v[6:7]
	flat_store_dword v[6:7], v8
	v_add_u32_e32 v6, 1, v4
	v_ashrrev_i32_e32 v7, 31, v6
	v_lshl_add_u64 v[8:9], v[6:7], 2, s[16:17]
	v_add_co_u32_e32 v14, vcc, s23, v8
	v_mov_b32_e32 v5, v184
	s_nop 0
	v_addc_co_u32_e32 v15, vcc, 0, v9, vcc
	v_mov_b32_e32 v14, v185
	v_lshlrev_b64 v[6:7], 6, v[6:7]
	v_lshl_add_u64 v[6:7], v[22:23], 0, v[6:7]
	v_add_f32_e32 v5, 0, v5
	v_add_f32_e32 v5, v5, v14
	v_add_co_u32_e32 v14, vcc, s78, v8
	s_nop 1
	v_addc_co_u32_e32 v15, vcc, 0, v9, vcc
	v_mov_b32_e32 v14, v186
	v_add_f32_e32 v5, v5, v14
	v_add_co_u32_e32 v14, vcc, s24, v8
	s_nop 1
	v_addc_co_u32_e32 v15, vcc, 0, v9, vcc
	v_mov_b32_e32 v14, v187
	v_add_f32_e32 v5, v5, v14
	v_add_co_u32_e32 v14, vcc, s25, v8
	s_nop 1
	v_addc_co_u32_e32 v15, vcc, 0, v9, vcc
	v_mov_b32_e32 v14, v188
	v_add_f32_e32 v5, v5, v14
	v_add_co_u32_e32 v14, vcc, s26, v8
	s_nop 1
	v_addc_co_u32_e32 v15, vcc, 0, v9, vcc
	v_mov_b32_e32 v14, v189
	v_add_f32_e32 v5, v5, v14
	v_add_co_u32_e32 v14, vcc, s27, v8
	s_nop 1
	v_addc_co_u32_e32 v15, vcc, 0, v9, vcc
	v_add_co_u32_e32 v8, vcc, s28, v8
	v_mov_b32_e32 v14, v190
	s_nop 0
	v_addc_co_u32_e32 v9, vcc, 0, v9, vcc
	v_mov_b32_e32 v8, v191
	v_add_f32_e32 v5, v5, v14
	v_add_f32_e32 v5, v5, v8
	v_fmamk_f32 v5, v5, 0x3a000000, v214
	v_cmp_gt_f32_e32 vcc, s79, v5
	v_mul_f32_e32 v8, 0x4f800000, v5
	s_nop 0
	v_cndmask_b32_e32 v5, v5, v8, vcc
	v_sqrt_f32_e32 v8, v5
	s_nop 0
	v_add_u32_e32 v9, -1, v8
	v_fma_f32 v14, -v9, v8, v5
	v_cmp_ge_f32_e64 s[4:5], 0, v14
	v_add_u32_e32 v14, 1, v8
	s_nop 0
	v_cndmask_b32_e64 v9, v8, v9, s[4:5]
	v_fma_f32 v8, -v14, v8, v5
	v_cmp_lt_f32_e64 s[4:5], 0, v8
	s_nop 1
	v_cndmask_b32_e64 v8, v9, v14, s[4:5]
	v_mul_f32_e32 v9, 0x37800000, v8
	v_cndmask_b32_e32 v8, v8, v9, vcc
	v_cmp_class_f32_e32 vcc, v5, v1
	s_nop 1
	v_cndmask_b32_e32 v5, v8, v5, vcc
	v_div_scale_f32 v8, s[4:5], v5, v5, v13
	v_rcp_f32_e32 v9, v8
	s_nop 0
	v_fma_f32 v14, -v8, v9, 1.0
	v_fmac_f32_e32 v9, v14, v9
	v_div_scale_f32 v14, vcc, v13, v5, v13
	v_mul_f32_e32 v15, v14, v9
	v_fma_f32 v16, -v8, v15, v14
	v_fmac_f32_e32 v15, v16, v9
	v_fma_f32 v8, -v8, v15, v14
	v_div_fmas_f32 v8, v8, v9, v15
	v_div_fixup_f32 v5, v8, v5, v13
	v_add_f32_e32 v5, v11, v5
	v_max_f32_e32 v8, 0, v5
	v_mul_f32_e64 v5, |v5|, s9
	v_exp_f32_e32 v5, v5
	s_nop 0
	v_add_f32_e32 v5, 1.0, v5
	v_log_f32_e32 v5, v5
	s_nop 0
	v_fmac_f32_e32 v8, 0x3f317218, v5
	flat_store_dword v[6:7], v8
	v_add_u32_e32 v6, 2, v4
	v_ashrrev_i32_e32 v7, 31, v6
	v_lshl_add_u64 v[8:9], v[6:7], 2, s[16:17]
	v_add_co_u32_e32 v14, vcc, s23, v8
	v_mov_b32_e32 v5, v192
	s_nop 0
	v_addc_co_u32_e32 v15, vcc, 0, v9, vcc
	v_mov_b32_e32 v13, v193
	v_add_co_u32_e32 v14, vcc, s78, v8
	v_lshlrev_b64 v[6:7], 6, v[6:7]
	s_nop 0
	v_addc_co_u32_e32 v15, vcc, 0, v9, vcc
	v_add_u32_e32 v4, 3, v4
	v_lshl_add_u64 v[6:7], v[22:23], 0, v[6:7]
	v_add_f32_e32 v5, 0, v5
	v_add_f32_e32 v5, v5, v13
	v_mov_b32_e32 v13, v194
	v_add_co_u32_e32 v14, vcc, s24, v8
	v_add_f32_e32 v5, v5, v13
	v_addc_co_u32_e32 v15, vcc, 0, v9, vcc
	v_mov_b32_e32 v13, v195
	v_add_co_u32_e32 v14, vcc, s25, v8
	v_add_f32_e32 v5, v5, v13
	v_addc_co_u32_e32 v15, vcc, 0, v9, vcc
	v_mov_b32_e32 v13, v196
	v_add_co_u32_e32 v14, vcc, s26, v8
	v_add_f32_e32 v5, v5, v13
	v_addc_co_u32_e32 v15, vcc, 0, v9, vcc
	v_mov_b32_e32 v13, v197
	v_add_co_u32_e32 v14, vcc, s27, v8
	v_add_f32_e32 v5, v5, v13
	v_addc_co_u32_e32 v15, vcc, 0, v9, vcc
	v_add_co_u32_e32 v8, vcc, s28, v8
	v_mov_b32_e32 v13, v198
	s_nop 0
	v_addc_co_u32_e32 v9, vcc, 0, v9, vcc
	v_mov_b32_e32 v8, v199
	v_add_f32_e32 v5, v5, v13
	v_add_f32_e32 v5, v5, v8
	v_fmamk_f32 v5, v5, 0x3a000000, v214
	v_cmp_gt_f32_e32 vcc, s79, v5
	v_mul_f32_e32 v8, 0x4f800000, v5
	s_nop 0
	v_cndmask_b32_e32 v5, v5, v8, vcc
	v_sqrt_f32_e32 v8, v5
	s_nop 0
	v_add_u32_e32 v9, -1, v8
	v_fma_f32 v13, -v9, v8, v5
	v_cmp_ge_f32_e64 s[4:5], 0, v13
	v_add_u32_e32 v13, 1, v8
	s_nop 0
	v_cndmask_b32_e64 v9, v8, v9, s[4:5]
	v_fma_f32 v8, -v13, v8, v5
	v_cmp_lt_f32_e64 s[4:5], 0, v8
	s_nop 1
	v_cndmask_b32_e64 v8, v9, v13, s[4:5]
	v_mul_f32_e32 v9, 0x37800000, v8
	v_cndmask_b32_e32 v8, v8, v9, vcc
	v_cmp_class_f32_e32 vcc, v5, v1
	s_nop 1
	v_cndmask_b32_e32 v5, v8, v5, vcc
	v_div_scale_f32 v8, s[4:5], v5, v5, v12
	v_rcp_f32_e32 v9, v8
	s_nop 0
	v_fma_f32 v13, -v8, v9, 1.0
	v_fmac_f32_e32 v9, v13, v9
	v_div_scale_f32 v13, vcc, v12, v5, v12
	v_mul_f32_e32 v14, v13, v9
	v_fma_f32 v15, -v8, v14, v13
	v_fmac_f32_e32 v14, v15, v9
	v_fma_f32 v8, -v8, v14, v13
	v_div_fmas_f32 v8, v8, v9, v14
	v_div_fixup_f32 v5, v8, v5, v12
	v_add_f32_e32 v5, v11, v5
	v_max_f32_e32 v8, 0, v5
	v_mul_f32_e64 v5, |v5|, s9
	v_exp_f32_e32 v5, v5
	s_nop 0
	v_add_f32_e32 v5, 1.0, v5
	v_log_f32_e32 v5, v5
	s_nop 0
	v_fmac_f32_e32 v8, 0x3f317218, v5
	v_ashrrev_i32_e32 v5, 31, v4
	flat_store_dword v[6:7], v8
	v_lshl_add_u64 v[6:7], v[4:5], 2, s[16:17]
	v_mov_b32_e32 v8, v200
	v_lshlrev_b64 v[4:5], 6, v[4:5]
	v_lshl_add_u64 v[4:5], v[22:23], 0, v[4:5]
	v_add_f32_e32 v12, 0, v8
	v_add_co_u32_e32 v8, vcc, s23, v6
	s_nop 1
	v_addc_co_u32_e32 v9, vcc, 0, v7, vcc
	v_mov_b32_e32 v8, v201
	v_add_f32_e32 v12, v12, v8
	v_add_co_u32_e32 v8, vcc, s78, v6
	s_nop 1
	v_addc_co_u32_e32 v9, vcc, 0, v7, vcc
	v_mov_b32_e32 v8, v202
	v_add_f32_e32 v12, v12, v8
	v_add_co_u32_e32 v8, vcc, s24, v6
	s_nop 1
	v_addc_co_u32_e32 v9, vcc, 0, v7, vcc
	v_mov_b32_e32 v8, v203
	v_add_f32_e32 v12, v12, v8
	v_add_co_u32_e32 v8, vcc, s25, v6
	s_nop 1
	v_addc_co_u32_e32 v9, vcc, 0, v7, vcc
	v_mov_b32_e32 v8, v204
	v_add_f32_e32 v12, v12, v8
	v_add_co_u32_e32 v8, vcc, s26, v6
	s_nop 1
	v_addc_co_u32_e32 v9, vcc, 0, v7, vcc
	v_mov_b32_e32 v8, v205
	v_add_f32_e32 v12, v12, v8
	v_add_co_u32_e32 v8, vcc, s27, v6
	s_nop 1
	v_addc_co_u32_e32 v9, vcc, 0, v7, vcc
	v_add_co_u32_e32 v6, vcc, s28, v6
	v_mov_b32_e32 v8, v206
	s_nop 0
	v_addc_co_u32_e32 v7, vcc, 0, v7, vcc
	v_mov_b32_e32 v6, v207
	v_add_f32_e32 v8, v12, v8
	v_add_f32_e32 v6, v8, v6
	v_fmamk_f32 v6, v6, 0x3a000000, v214
	v_cmp_gt_f32_e32 vcc, s79, v6
	v_mul_f32_e32 v7, 0x4f800000, v6
	s_nop 0
	v_cndmask_b32_e32 v6, v6, v7, vcc
	v_sqrt_f32_e32 v7, v6
	s_nop 0
	v_add_u32_e32 v8, -1, v7
	v_fma_f32 v9, -v8, v7, v6
	v_cmp_ge_f32_e64 s[4:5], 0, v9
	v_add_u32_e32 v9, 1, v7
	s_nop 0
	v_cndmask_b32_e64 v8, v7, v8, s[4:5]
	v_fma_f32 v7, -v9, v7, v6
	v_cmp_lt_f32_e64 s[4:5], 0, v7
	s_nop 1
	v_cndmask_b32_e64 v7, v8, v9, s[4:5]
	v_mul_f32_e32 v8, 0x37800000, v7
	v_cndmask_b32_e32 v7, v7, v8, vcc
	v_cmp_class_f32_e32 vcc, v6, v1
	s_nop 1
	v_cndmask_b32_e32 v6, v7, v6, vcc
	v_div_scale_f32 v7, s[4:5], v6, v6, v10
	v_rcp_f32_e32 v8, v7
	s_nop 0
	v_fma_f32 v9, -v7, v8, 1.0
	v_fmac_f32_e32 v8, v9, v8
	v_div_scale_f32 v9, vcc, v10, v6, v10
	v_mul_f32_e32 v12, v9, v8
	v_fma_f32 v13, -v7, v12, v9
	v_fmac_f32_e32 v12, v13, v8
	v_fma_f32 v7, -v7, v12, v9
	v_div_fmas_f32 v7, v7, v8, v12
	v_div_fixup_f32 v6, v7, v6, v10
	v_add_f32_e32 v6, v11, v6
	v_max_f32_e32 v7, 0, v6
	v_mul_f32_e64 v6, |v6|, s9
	v_exp_f32_e32 v6, v6
	s_nop 0
	v_add_f32_e32 v6, 1.0, v6
	v_log_f32_e32 v6, v6
	s_nop 0
	v_fmac_f32_e32 v7, 0x3f317218, v6
	flat_store_dword v[4:5], v7
	s_branch .LBB0_265

.LBB0_1475:
	v_lshl_add_u64 v[12:13], s[8:9], 0, v[20:21]
	v_add_co_u32_e32 v4, vcc, 0x2840f000, v12
	v_lshl_add_u64 v[14:15], s[6:7], 0, v[20:21]
	s_nop 0
	v_addc_co_u32_e32 v5, vcc, 0, v13, vcc
	v_add_co_u32_e32 v8, vcc, 0x2841a000, v12
	global_load_dwordx4 v[4:7], v[4:5], off offset:2048
	s_nop 0
	v_addc_co_u32_e32 v9, vcc, 0, v13, vcc
	global_load_dwordx4 v[24:27], v[8:9], off offset:2048
	v_add_co_u32_e32 v8, vcc, 0x283f9000, v14
	v_lshl_add_u64 v[64:65], s[14:15], 0, v[20:21]
	s_nop 0
	v_addc_co_u32_e32 v9, vcc, 0, v15, vcc
	global_load_dwordx4 v[28:31], v[8:9], off offset:2048
	v_add_co_u32_e32 v8, vcc, 0x28404000, v14
	global_load_dwordx4 v[40:43], v[64:65], off
	s_nop 0
	v_addc_co_u32_e32 v9, vcc, 0, v15, vcc
	v_add_co_u32_e32 v16, vcc, 0x28415000, v12
	v_lshl_add_u64 v[68:69], s[12:13], 0, v[20:21]
	v_addc_co_u32_e32 v17, vcc, 0, v13, vcc
	v_add_co_u32_e32 v12, vcc, 0x28420000, v12
	global_load_dwordx4 v[16:19], v[16:17], off
	s_nop 0
	v_addc_co_u32_e32 v13, vcc, 0, v13, vcc
	global_load_dwordx4 v[32:35], v[12:13], off
	v_add_co_u32_e32 v12, vcc, 0x283ff000, v14
	global_load_dwordx4 v[52:55], v[68:69], off
	s_nop 0
	v_addc_co_u32_e32 v13, vcc, 0, v15, vcc
	global_load_dwordx4 v[36:39], v[12:13], off
	v_add_co_u32_e32 v12, vcc, 0x2840a000, v14
	global_load_dwordx4 v[8:11], v[8:9], off offset:2048
	s_nop 0
	v_addc_co_u32_e32 v13, vcc, 0, v15, vcc
	v_add_co_u32_e32 v44, vcc, s81, v64
	global_load_dwordx4 v[12:15], v[12:13], off
	s_nop 0
	v_addc_co_u32_e32 v45, vcc, 0, v65, vcc
	v_add_co_u32_e32 v48, vcc, s82, v64
	global_load_dwordx4 v[44:47], v[44:45], off
	s_nop 0
	v_addc_co_u32_e32 v49, vcc, 0, v65, vcc
	v_add_co_u32_e32 v56, vcc, s84, v64
	global_load_dwordx4 v[48:51], v[48:49], off
	s_nop 0
	v_addc_co_u32_e32 v57, vcc, 0, v65, vcc
	v_add_co_u32_e32 v60, vcc, s78, v64
	global_load_dwordx4 v[56:59], v[56:57], off offset:2048
	s_nop 0
	v_addc_co_u32_e32 v61, vcc, 0, v65, vcc
	v_add_co_u32_e32 v64, vcc, s85, v64
	global_load_dwordx4 v[60:63], v[60:61], off offset:2048
	s_nop 0
	v_addc_co_u32_e32 v65, vcc, 0, v65, vcc
	v_add_co_u32_e32 v68, vcc, s84, v68
	global_load_dwordx4 v[64:67], v[64:65], off offset:2048
	s_nop 0
	v_addc_co_u32_e32 v69, vcc, 0, v69, vcc
	global_load_dwordx4 v[68:71], v[68:69], off offset:2048
	s_add_u32 s14, s14, 0x2000
	s_addc_u32 s15, s15, 0
	s_add_u32 s12, s12, 0x2000
	s_addc_u32 s13, s13, 0
	s_movk_i32 s19, 0xe000
	s_add_u32 s6, s6, 0x2000
	s_addc_u32 s7, s7, 0
	v_add_u32_e32 v2, 0x800, v2
	s_add_u32 s8, s8, 0x2000
	s_addc_u32 s9, s9, 0
	s_waitcnt vmcnt(5)
	v_pk_mul_f32 v[72:73], v[26:27], v[46:47]
	v_pk_fma_f32 v[26:27], v[26:27], v[42:43], v[54:55]
	v_pk_mul_f32 v[74:75], v[24:25], v[44:45]
	v_pk_fma_f32 v[24:25], v[24:25], v[40:41], v[52:53]
	v_pk_fma_f32 v[26:27], v[30:31], v[46:47], v[26:27]
	s_waitcnt vmcnt(4)
	v_pk_mul_f32 v[76:77], v[30:31], v[50:51]
	v_pk_mul_f32 v[78:79], v[28:29], v[48:49]
	v_pk_fma_f32 v[24:25], v[28:29], v[44:45], v[24:25]
	s_waitcnt vmcnt(2)
	v_pk_mul_f32 v[80:81], v[34:35], v[62:63]
	v_pk_mul_f32 v[82:83], v[32:33], v[60:61]
	s_waitcnt vmcnt(1)
	v_pk_mul_f32 v[86:87], v[36:37], v[64:65]
	v_pk_mul_f32 v[84:85], v[38:39], v[66:67]
	s_waitcnt vmcnt(0)
	v_pk_fma_f32 v[30:31], v[32:33], v[56:57], v[68:69]
	v_pk_fma_f32 v[28:29], v[34:35], v[58:59], v[70:71]
	v_pk_fma_f32 v[30:31], v[36:37], v[60:61], v[30:31]
	v_mov_b32_e32 v32, v16
	v_mov_b32_e32 v33, v4
	v_mov_b32_e32 v34, v56
	v_mov_b32_e32 v35, v40
	v_mov_b32_e32 v36, v68
	v_mov_b32_e32 v37, v52
	v_pk_fma_f32 v[32:33], v[32:33], v[34:35], v[36:37]
	v_mov_b32_e32 v34, v82
	v_mov_b32_e32 v35, v74
	v_pk_add_f32 v[32:33], v[34:35], v[32:33]
	v_mov_b32_e32 v34, v86
	v_mov_b32_e32 v35, v78
	v_pk_add_f32 v[32:33], v[34:35], v[32:33]
	v_mov_b32_e32 v34, v64
	v_mul_f32_e32 v4, 0xbfb8aa3b, v33
	v_exp_f32_e32 v4, v4
	v_mov_b32_e32 v35, v48
	v_mov_b32_e32 v36, v30
	v_mov_b32_e32 v37, v24
	v_add_f32_e32 v4, 1.0, v4
	v_rcp_f32_e32 v4, v4
	v_mov_b32_e32 v40, v57
	v_mov_b32_e32 v52, v69
	v_mov_b32_e32 v74, v83
	v_mul_f32_e32 v4, v33, v4
	v_mul_f32_e32 v16, v32, v4
	v_mov_b32_e32 v32, v12
	v_mov_b32_e32 v33, v8
	v_pk_fma_f32 v[32:33], v[32:33], v[34:35], v[36:37]
	v_mov_b32_e32 v78, v87
	v_mul_f32_e32 v4, 0xbfb8aa3b, v33
	v_exp_f32_e32 v4, v4
	v_mov_b32_e32 v48, v65
	v_mov_b32_e32 v24, v31
	v_mov_b32_e32 v12, v70
	v_add_f32_e32 v4, 1.0, v4
	v_rcp_f32_e32 v4, v4
	v_pk_fma_f32 v[28:29], v[38:39], v[62:63], v[28:29]
	v_mul_f32_e32 v4, v33, v4
	v_mul_f32_e32 v30, v32, v4
	v_mov_b32_e32 v4, v17
	v_pk_fma_f32 v[4:5], v[4:5], v[40:41], v[52:53]
	s_nop 0
	v_pk_add_f32 v[4:5], v[74:75], v[4:5]
	s_nop 0
	v_pk_add_f32 v[4:5], v[78:79], v[4:5]
	s_nop 0
	v_mul_f32_e32 v8, 0xbfb8aa3b, v5
	v_exp_f32_e32 v8, v8
	s_nop 0
	v_add_f32_e32 v8, 1.0, v8
	v_rcp_f32_e32 v8, v8
	s_nop 0
	v_mul_f32_e32 v5, v5, v8
	v_mov_b32_e32 v8, v13
	v_mul_f32_e32 v17, v4, v5
	v_pk_fma_f32 v[4:5], v[8:9], v[48:49], v[24:25]
	v_mov_b32_e32 v9, v42
	v_mul_f32_e32 v8, 0xbfb8aa3b, v5
	v_exp_f32_e32 v8, v8
	v_mov_b32_e32 v13, v54
	v_mov_b32_e32 v42, v59
	v_mov_b32_e32 v54, v71
	v_add_f32_e32 v8, 1.0, v8
	v_rcp_f32_e32 v8, v8
	s_nop 0
	v_mul_f32_e32 v5, v5, v8
	v_mul_f32_e32 v24, v4, v5
	v_mov_b32_e32 v4, v18
	v_mov_b32_e32 v5, v6
	v_mov_b32_e32 v8, v58
	v_pk_fma_f32 v[4:5], v[4:5], v[8:9], v[12:13]
	v_mov_b32_e32 v8, v80
	v_mov_b32_e32 v9, v72
	v_pk_add_f32 v[4:5], v[8:9], v[4:5]
	v_mov_b32_e32 v8, v84
	v_mov_b32_e32 v9, v76
	v_pk_add_f32 v[4:5], v[8:9], v[4:5]
	v_mov_b32_e32 v8, v66
	v_mul_f32_e32 v6, 0xbfb8aa3b, v5
	v_exp_f32_e32 v6, v6
	v_mov_b32_e32 v9, v50
	v_mov_b32_e32 v12, v28
	v_mov_b32_e32 v13, v26
	v_add_f32_e32 v6, 1.0, v6
	v_rcp_f32_e32 v6, v6
	v_mov_b32_e32 v72, v81
	v_mov_b32_e32 v76, v85
	v_mov_b32_e32 v50, v67
	v_mul_f32_e32 v5, v5, v6
	v_mul_f32_e32 v18, v4, v5
	v_mov_b32_e32 v4, v14
	v_mov_b32_e32 v5, v10
	v_pk_fma_f32 v[4:5], v[4:5], v[8:9], v[12:13]
	v_mov_b32_e32 v10, v15
	v_mul_f32_e32 v6, 0xbfb8aa3b, v5
	v_exp_f32_e32 v6, v6
	v_mov_b32_e32 v26, v29
	v_add_f32_e32 v6, 1.0, v6
	v_rcp_f32_e32 v6, v6
	s_nop 0
	v_mul_f32_e32 v5, v5, v6
	v_mov_b32_e32 v6, v19
	v_mul_f32_e32 v8, v4, v5
	v_pk_fma_f32 v[4:5], v[6:7], v[42:43], v[54:55]
	s_nop 0
	v_pk_add_f32 v[4:5], v[72:73], v[4:5]
	s_nop 0
	v_pk_add_f32 v[4:5], v[76:77], v[4:5]
	s_nop 0
	v_mul_f32_e32 v6, 0xbfb8aa3b, v5
	v_exp_f32_e32 v6, v6
	s_nop 0
	v_add_f32_e32 v6, 1.0, v6
	v_rcp_f32_e32 v6, v6
	s_nop 0
	v_mul_f32_e32 v5, v5, v6
	v_mul_f32_e32 v6, v4, v5
	v_pk_fma_f32 v[4:5], v[10:11], v[50:51], v[26:27]
	s_nop 0
	v_mul_f32_e32 v7, 0xbfb8aa3b, v5
	v_exp_f32_e32 v7, v7
	s_nop 0
	v_add_f32_e32 v7, 1.0, v7
	v_rcp_f32_e32 v7, v7
	s_nop 0
	v_mul_f32_e32 v5, v5, v7
	v_mul_f32_e32 v7, v4, v5
	v_cvt_pk_bf16_f32 v7, v8, v7
	v_add_co_u32_e32 v8, vcc, s19, v22
	s_movk_i32 s19, 0xdff
	s_nop 0
	v_addc_co_u32_e32 v9, vcc, -1, v23, vcc
	v_cvt_pk_bf16_f32 v4, v16, v17
	v_cvt_pk_bf16_f32 v5, v18, v6
	v_cmp_lt_i32_e32 vcc, s19, v2
	v_cvt_pk_bf16_f32 v6, v30, v24
	global_store_dwordx2 v[8:9], v[4:5], off offset:-3072
	global_store_dwordx2 v[22:23], v[6:7], off
	v_lshl_add_u64 v[22:23], v[22:23], 0, s[20:21]
	s_or_b64 s[10:11], vcc, s[10:11]
	s_andn2_b64 exec, exec, s[10:11]
	s_cbranch_execnz .LBB0_1475
	s_branch .LBB0_1462

.LBB0_1480:
	s_mov_b32 s23, s13
	s_ashr_i32 s13, s12, 31
	s_lshl_b64 s[24:25], s[12:13], 1
	v_lshl_add_u64 v[44:45], v[144:145], 0, s[24:25]
	v_add_co_u32_e32 v28, vcc, s82, v44
	v_lshl_add_u64 v[48:49], v[156:157], 0, s[24:25]
	s_nop 0
	v_addc_co_u32_e32 v29, vcc, 0, v45, vcc
	v_add_co_u32_e32 v32, vcc, s82, v48
	global_load_dwordx4 v[20:23], v[44:45], off
	global_load_dwordx4 v[24:27], v[48:49], off
	v_addc_co_u32_e32 v33, vcc, 0, v49, vcc
	v_add_co_u32_e32 v36, vcc, s39, v44
	global_load_dwordx4 v[28:31], v[28:29], off
	s_nop 0
	v_addc_co_u32_e32 v37, vcc, 0, v45, vcc
	v_add_co_u32_e32 v40, vcc, s39, v48
	global_load_dwordx4 v[32:35], v[32:33], off
	s_nop 0
	v_addc_co_u32_e32 v41, vcc, 0, v49, vcc
	v_add_co_u32_e32 v44, vcc, s41, v44
	global_load_dwordx4 v[36:39], v[36:37], off
	s_nop 0
	v_addc_co_u32_e32 v45, vcc, 0, v45, vcc
	global_load_dwordx4 v[40:43], v[40:41], off
	v_add_co_u32_e32 v48, vcc, s41, v48
	global_load_dwordx4 v[44:47], v[44:45], off
	s_nop 0
	v_addc_co_u32_e32 v49, vcc, 0, v49, vcc
	global_load_dwordx4 v[48:51], v[48:49], off
	s_add_i32 s24, s12, 64
	s_ashr_i32 s25, s24, 31
	s_lshl_b64 s[24:25], s[24:25], 1
	v_lshl_add_u64 v[76:77], v[144:145], 0, s[24:25]
	v_add_co_u32_e32 v52, vcc, s82, v76
	v_lshl_add_u64 v[80:81], v[156:157], 0, s[24:25]
	s_nop 0
	v_addc_co_u32_e32 v53, vcc, 0, v77, vcc
	v_add_co_u32_e32 v64, vcc, s82, v80
	global_load_dwordx4 v[56:59], v[76:77], off
	global_load_dwordx4 v[60:63], v[80:81], off
	v_addc_co_u32_e32 v65, vcc, 0, v81, vcc
	v_add_co_u32_e32 v68, vcc, s39, v76
	global_load_dwordx4 v[52:55], v[52:53], off
	s_nop 0
	v_addc_co_u32_e32 v69, vcc, 0, v77, vcc
	v_add_co_u32_e32 v72, vcc, s39, v80
	global_load_dwordx4 v[64:67], v[64:65], off
	s_nop 0
	v_addc_co_u32_e32 v73, vcc, 0, v81, vcc
	v_add_co_u32_e32 v76, vcc, s41, v76
	global_load_dwordx4 v[68:71], v[68:69], off
	s_nop 0
	v_addc_co_u32_e32 v77, vcc, 0, v77, vcc
	global_load_dwordx4 v[72:75], v[72:73], off
	v_add_co_u32_e32 v80, vcc, s41, v80
	global_load_dwordx4 v[76:79], v[76:77], off
	s_nop 0
	v_addc_co_u32_e32 v81, vcc, 0, v81, vcc
	global_load_dwordx4 v[80:83], v[80:81], off
	s_add_i32 s24, s12, 0x80
	s_ashr_i32 s25, s24, 31
	s_lshl_b64 s[24:25], s[24:25], 1
	v_lshl_add_u64 v[108:109], v[144:145], 0, s[24:25]
	v_add_co_u32_e32 v84, vcc, s82, v108
	v_lshl_add_u64 v[112:113], v[156:157], 0, s[24:25]
	s_nop 0
	v_addc_co_u32_e32 v85, vcc, 0, v109, vcc
	v_add_co_u32_e32 v96, vcc, s82, v112
	global_load_dwordx4 v[88:91], v[108:109], off
	global_load_dwordx4 v[92:95], v[112:113], off
	v_addc_co_u32_e32 v97, vcc, 0, v113, vcc
	v_add_co_u32_e32 v100, vcc, s39, v108
	s_add_i32 s24, s12, 0xc0
	s_nop 0
	v_addc_co_u32_e32 v101, vcc, 0, v109, vcc
	v_add_co_u32_e32 v104, vcc, s39, v112
	s_ashr_i32 s25, s24, 31
	s_nop 0
	v_addc_co_u32_e32 v105, vcc, 0, v113, vcc
	v_add_co_u32_e32 v108, vcc, s41, v108
	global_load_dwordx4 v[84:87], v[84:85], off
	s_nop 0
	v_addc_co_u32_e32 v109, vcc, 0, v109, vcc
	v_add_co_u32_e32 v112, vcc, s41, v112
	s_lshl_b64 s[24:25], s[24:25], 1
	global_load_dwordx4 v[96:99], v[96:97], off
	v_addc_co_u32_e32 v113, vcc, 0, v113, vcc
	v_lshl_add_u64 v[140:141], v[144:145], 0, s[24:25]
	global_load_dwordx4 v[100:103], v[100:101], off
	v_add_co_u32_e32 v116, vcc, s82, v140
	global_load_dwordx4 v[104:107], v[104:105], off
	v_lshl_add_u64 v[162:163], v[156:157], 0, s[24:25]
	v_addc_co_u32_e32 v117, vcc, 0, v141, vcc
	global_load_dwordx4 v[108:111], v[108:109], off
	v_add_co_u32_e32 v128, vcc, s82, v162
	global_load_dwordx4 v[112:115], v[112:113], off
	s_nop 0
	v_addc_co_u32_e32 v129, vcc, 0, v163, vcc
	v_add_co_u32_e32 v132, vcc, s39, v140
	global_load_dwordx4 v[120:123], v[140:141], off
	global_load_dwordx4 v[124:127], v[162:163], off
	v_addc_co_u32_e32 v133, vcc, 0, v141, vcc
	v_add_co_u32_e32 v136, vcc, s39, v162
	global_load_dwordx4 v[116:119], v[116:117], off
	s_nop 0
	v_addc_co_u32_e32 v137, vcc, 0, v163, vcc
	v_add_co_u32_e32 v140, vcc, s41, v140
	global_load_dwordx4 v[128:131], v[128:129], off
	s_nop 0
	v_addc_co_u32_e32 v141, vcc, 0, v141, vcc
	v_add_co_u32_e32 v162, vcc, s41, v162
	global_load_dwordx4 v[132:135], v[132:133], off
	s_nop 0
	v_addc_co_u32_e32 v163, vcc, 0, v163, vcc
	global_load_dwordx4 v[136:139], v[136:137], off
	s_add_i32 s13, s23, 4
	global_load_dwordx4 v[140:143], v[140:141], off
	s_addk_i32 s12, 0x100
	global_load_dwordx4 v[162:165], v[162:163], off
	s_waitcnt vmcnt(24)
	ds_write_b128 v2, v[20:23]
	ds_write_b128 v2, v[24:27] offset:4608
	ds_write_b128 v2, v[28:31] offset:1152
	ds_write_b128 v2, v[32:35] offset:5760
	ds_write_b128 v2, v[36:39] offset:2304
	ds_write_b128 v2, v[40:43] offset:6912
	ds_write_b128 v2, v[44:47] offset:3456
	ds_write_b128 v2, v[48:51] offset:8064
	s_waitcnt lgkmcnt(0)
	ds_read_b128 v[20:23], v160 offset:4608
	ds_read_b128 v[24:27], v160
	ds_read_b128 v[28:31], v160 offset:16
	ds_read_b128 v[32:35], v160 offset:32
	ds_read_b128 v[36:39], v160 offset:48
	s_waitcnt lgkmcnt(3)
	v_mfma_f32_32x32x16_bf16 v[4:19], v[24:27], v[20:23], v[4:19]
	ds_read_b128 v[20:23], v160 offset:4624
	s_cmp_ge_i32 s23, s18
	s_waitcnt lgkmcnt(0)
	v_mfma_f32_32x32x16_bf16 v[4:19], v[28:31], v[20:23], v[4:19]
	ds_read_b128 v[20:23], v160 offset:4640
	s_waitcnt lgkmcnt(0)
	v_mfma_f32_32x32x16_bf16 v[4:19], v[32:35], v[20:23], v[4:19]
	ds_read_b128 v[20:23], v160 offset:4656
	s_waitcnt vmcnt(23)
	ds_write_b128 v2, v[56:59]
	s_waitcnt vmcnt(22)
	ds_write_b128 v2, v[60:63] offset:4608
	s_waitcnt vmcnt(21)
	ds_write_b128 v2, v[52:55] offset:1152
	s_waitcnt vmcnt(20)
	ds_write_b128 v2, v[64:67] offset:5760
	s_waitcnt vmcnt(19)
	ds_write_b128 v2, v[68:71] offset:2304
	s_waitcnt vmcnt(18)
	ds_write_b128 v2, v[72:75] offset:6912
	s_waitcnt vmcnt(17)
	ds_write_b128 v2, v[76:79] offset:3456
	s_waitcnt vmcnt(16)
	ds_write_b128 v2, v[80:83] offset:8064
	s_waitcnt lgkmcnt(0)
	s_waitcnt lgkmcnt(8)
	v_mfma_f32_32x32x16_bf16 v[4:19], v[36:39], v[20:23], v[4:19]
	ds_read_b128 v[20:23], v160 offset:4608
	ds_read_b128 v[24:27], v160
	ds_read_b128 v[28:31], v160 offset:16
	ds_read_b128 v[32:35], v160 offset:32
	ds_read_b128 v[36:39], v160 offset:48
	s_waitcnt lgkmcnt(3)
	v_mfma_f32_32x32x16_bf16 v[4:19], v[24:27], v[20:23], v[4:19]
	ds_read_b128 v[20:23], v160 offset:4624
	s_waitcnt lgkmcnt(0)
	v_mfma_f32_32x32x16_bf16 v[4:19], v[28:31], v[20:23], v[4:19]
	ds_read_b128 v[20:23], v160 offset:4640
	s_waitcnt lgkmcnt(0)
	v_mfma_f32_32x32x16_bf16 v[4:19], v[32:35], v[20:23], v[4:19]
	ds_read_b128 v[20:23], v160 offset:4656
	s_waitcnt vmcnt(15)
	ds_write_b128 v2, v[88:91]
	s_waitcnt vmcnt(14)
	ds_write_b128 v2, v[92:95] offset:4608
	s_waitcnt vmcnt(13)
	ds_write_b128 v2, v[84:87] offset:1152
	s_waitcnt vmcnt(12)
	ds_write_b128 v2, v[96:99] offset:5760
	s_waitcnt vmcnt(11)
	ds_write_b128 v2, v[100:103] offset:2304
	s_waitcnt vmcnt(10)
	ds_write_b128 v2, v[104:107] offset:6912
	s_waitcnt vmcnt(9)
	ds_write_b128 v2, v[108:111] offset:3456
	s_waitcnt vmcnt(8)
	ds_write_b128 v2, v[112:115] offset:8064
	s_waitcnt lgkmcnt(0)
	s_waitcnt lgkmcnt(8)
	v_mfma_f32_32x32x16_bf16 v[4:19], v[36:39], v[20:23], v[4:19]
	ds_read_b128 v[20:23], v160 offset:4608
	ds_read_b128 v[24:27], v160
	ds_read_b128 v[28:31], v160 offset:16
	ds_read_b128 v[32:35], v160 offset:32
	ds_read_b128 v[36:39], v160 offset:48
	s_waitcnt lgkmcnt(3)
	v_mfma_f32_32x32x16_bf16 v[4:19], v[24:27], v[20:23], v[4:19]
	ds_read_b128 v[20:23], v160 offset:4624
	s_waitcnt lgkmcnt(0)
	v_mfma_f32_32x32x16_bf16 v[4:19], v[28:31], v[20:23], v[4:19]
	ds_read_b128 v[20:23], v160 offset:4640
	s_waitcnt lgkmcnt(0)
	v_mfma_f32_32x32x16_bf16 v[4:19], v[32:35], v[20:23], v[4:19]
	ds_read_b128 v[20:23], v160 offset:4656
	s_waitcnt vmcnt(7)
	ds_write_b128 v2, v[120:123]
	s_waitcnt vmcnt(6)
	ds_write_b128 v2, v[124:127] offset:4608
	s_waitcnt vmcnt(5)
	ds_write_b128 v2, v[116:119] offset:1152
	s_waitcnt vmcnt(4)
	ds_write_b128 v2, v[128:131] offset:5760
	s_waitcnt vmcnt(3)
	ds_write_b128 v2, v[132:135] offset:2304
	s_waitcnt vmcnt(2)
	ds_write_b128 v2, v[136:139] offset:6912
	s_waitcnt vmcnt(1)
	ds_write_b128 v2, v[140:143] offset:3456
	s_waitcnt vmcnt(0)
	ds_write_b128 v2, v[162:165] offset:8064
	s_waitcnt lgkmcnt(0)
	s_waitcnt lgkmcnt(8)
	v_mfma_f32_32x32x16_bf16 v[4:19], v[36:39], v[20:23], v[4:19]
	ds_read_b128 v[20:23], v160 offset:4608
	ds_read_b128 v[24:27], v160
	ds_read_b128 v[28:31], v160 offset:16
	ds_read_b128 v[32:35], v160 offset:32
	ds_read_b128 v[36:39], v160 offset:48
	s_waitcnt lgkmcnt(3)
	v_mfma_f32_32x32x16_bf16 v[4:19], v[24:27], v[20:23], v[4:19]
	ds_read_b128 v[20:23], v160 offset:4624
	s_waitcnt lgkmcnt(0)
	v_mfma_f32_32x32x16_bf16 v[4:19], v[28:31], v[20:23], v[4:19]
	ds_read_b128 v[20:23], v160 offset:4640
	s_waitcnt lgkmcnt(0)
	v_mfma_f32_32x32x16_bf16 v[4:19], v[32:35], v[20:23], v[4:19]
	ds_read_b128 v[20:23], v160 offset:4656
	s_waitcnt lgkmcnt(0)
	v_mfma_f32_32x32x16_bf16 v[4:19], v[36:39], v[20:23], v[4:19]
	s_cbranch_scc0 .LBB0_1480
	s_cmp_ge_i32 s23, s19
	s_cbranch_scc1 .LBB0_1483
	s_lshl_b32 s12, s13, 6
	s_ashr_i32 s13, s12, 31
	s_lshl_b64 s[24:25], s[12:13], 1
	v_lshl_add_u64 v[44:45], v[144:145], 0, s[24:25]
	v_add_co_u32_e32 v28, vcc, 0x16000, v44
	v_lshl_add_u64 v[46:47], v[156:157], 0, s[24:25]
	s_nop 0
	v_addc_co_u32_e32 v29, vcc, 0, v45, vcc
	v_add_co_u32_e32 v32, vcc, 0x16000, v46
	global_load_dwordx4 v[20:23], v[44:45], off
	global_load_dwordx4 v[24:27], v[46:47], off
	v_addc_co_u32_e32 v33, vcc, 0, v47, vcc
	v_add_co_u32_e32 v36, vcc, 0x2c000, v44
	global_load_dwordx4 v[28:31], v[28:29], off
	s_nop 0
	global_load_dwordx4 v[32:35], v[32:33], off
	v_addc_co_u32_e32 v37, vcc, 0, v45, vcc
	v_add_co_u32_e32 v40, vcc, 0x2c000, v46
	s_add_i32 s12, s12, 64
	s_nop 0
	v_addc_co_u32_e32 v41, vcc, 0, v47, vcc
	v_add_co_u32_e32 v44, vcc, 0x42000, v44
	global_load_dwordx4 v[36:39], v[36:37], off
	s_nop 0
	global_load_dwordx4 v[40:43], v[40:41], off
	v_addc_co_u32_e32 v45, vcc, 0, v45, vcc
	v_add_co_u32_e32 v48, vcc, 0x42000, v46
	s_ashr_i32 s13, s12, 31
	s_nop 0
	v_addc_co_u32_e32 v49, vcc, 0, v47, vcc
	global_load_dwordx4 v[44:47], v[44:45], off
	s_nop 0
	global_load_dwordx4 v[48:51], v[48:49], off
	s_lshl_b64 s[12:13], s[12:13], 1
	v_lshl_add_u64 v[76:77], v[144:145], 0, s[12:13]
	v_add_co_u32_e32 v60, vcc, s82, v76
	v_lshl_add_u64 v[78:79], v[156:157], 0, s[12:13]
	s_nop 0
	v_addc_co_u32_e32 v61, vcc, 0, v77, vcc
	v_add_co_u32_e32 v64, vcc, s82, v78
	global_load_dwordx4 v[52:55], v[76:77], off
	global_load_dwordx4 v[56:59], v[78:79], off
	v_addc_co_u32_e32 v65, vcc, 0, v79, vcc
	v_add_co_u32_e32 v68, vcc, s39, v76
	global_load_dwordx4 v[60:63], v[60:61], off
	s_nop 0
	global_load_dwordx4 v[64:67], v[64:65], off
	v_addc_co_u32_e32 v69, vcc, 0, v77, vcc
	v_add_co_u32_e32 v72, vcc, s39, v78
	s_add_i32 s13, s23, 6
	s_nop 0
	v_addc_co_u32_e32 v73, vcc, 0, v79, vcc
	v_add_co_u32_e32 v76, vcc, s41, v76
	global_load_dwordx4 v[68:71], v[68:69], off
	s_nop 0
	global_load_dwordx4 v[72:75], v[72:73], off
	v_addc_co_u32_e32 v77, vcc, 0, v77, vcc
	v_add_co_u32_e32 v80, vcc, s41, v78
	s_nop 1
	v_addc_co_u32_e32 v81, vcc, 0, v79, vcc
	global_load_dwordx4 v[76:79], v[76:77], off
	s_nop 0
	global_load_dwordx4 v[80:83], v[80:81], off
	s_waitcnt vmcnt(15)
	ds_write_b128 v2, v[20:23]
	s_waitcnt vmcnt(14)
	ds_write_b128 v2, v[24:27] offset:4608
	s_waitcnt vmcnt(13)
	ds_write_b128 v2, v[28:31] offset:1152
	s_waitcnt vmcnt(12)
	ds_write_b128 v2, v[32:35] offset:5760
	s_waitcnt vmcnt(11)
	ds_write_b128 v2, v[36:39] offset:2304
	s_waitcnt vmcnt(10)
	ds_write_b128 v2, v[40:43] offset:6912
	s_waitcnt vmcnt(9)
	ds_write_b128 v2, v[44:47] offset:3456
	s_waitcnt vmcnt(8)
	ds_write_b128 v2, v[48:51] offset:8064
	s_waitcnt lgkmcnt(0)
	ds_read_b128 v[20:23], v160
	ds_read_b128 v[24:27], v160 offset:4608
	ds_read_b128 v[28:31], v160 offset:16
	ds_read_b128 v[32:35], v160 offset:4624
	s_waitcnt lgkmcnt(2)
	v_mfma_f32_32x32x16_bf16 v[4:19], v[20:23], v[24:27], v[4:19]
	s_waitcnt lgkmcnt(0)
	v_mfma_f32_32x32x16_bf16 v[4:19], v[28:31], v[32:35], v[4:19]
	ds_read_b128 v[20:23], v160 offset:32
	ds_read_b128 v[24:27], v160 offset:4640
	ds_read_b128 v[28:31], v160 offset:48
	ds_read_b128 v[32:35], v160 offset:4656
	s_waitcnt vmcnt(7)
	ds_write_b128 v2, v[52:55]
	s_waitcnt vmcnt(6)
	ds_write_b128 v2, v[56:59] offset:4608
	s_waitcnt vmcnt(5)
	ds_write_b128 v2, v[60:63] offset:1152
	s_waitcnt vmcnt(4)
	ds_write_b128 v2, v[64:67] offset:5760
	s_waitcnt vmcnt(3)
	ds_write_b128 v2, v[68:71] offset:2304
	s_waitcnt vmcnt(2)
	ds_write_b128 v2, v[72:75] offset:6912
	s_waitcnt vmcnt(1)
	ds_write_b128 v2, v[76:79] offset:3456
	s_waitcnt vmcnt(0)
	ds_write_b128 v2, v[80:83] offset:8064
	s_waitcnt lgkmcnt(10)
	v_mfma_f32_32x32x16_bf16 v[4:19], v[20:23], v[24:27], v[4:19]
	s_waitcnt lgkmcnt(0)
	s_waitcnt lgkmcnt(8)
	v_mfma_f32_32x32x16_bf16 v[4:19], v[28:31], v[32:35], v[4:19]
	ds_read_b128 v[20:23], v160
	ds_read_b128 v[24:27], v160 offset:4608
	ds_read_b128 v[28:31], v160 offset:16
	ds_read_b128 v[32:35], v160 offset:4624
	s_waitcnt lgkmcnt(2)
	v_mfma_f32_32x32x16_bf16 v[4:19], v[20:23], v[24:27], v[4:19]
	s_waitcnt lgkmcnt(0)
	v_mfma_f32_32x32x16_bf16 v[4:19], v[28:31], v[32:35], v[4:19]
	ds_read_b128 v[20:23], v160 offset:32
	ds_read_b128 v[24:27], v160 offset:4640
	ds_read_b128 v[28:31], v160 offset:48
	ds_read_b128 v[32:35], v160 offset:4656
	s_waitcnt lgkmcnt(2)
	v_mfma_f32_32x32x16_bf16 v[4:19], v[20:23], v[24:27], v[4:19]
	s_waitcnt lgkmcnt(0)
	v_mfma_f32_32x32x16_bf16 v[4:19], v[28:31], v[32:35], v[4:19]
